# diff attention tile loop: K/Q/V fragment LDS reads software-pipelined ahead of their MFMAs (4 buffers) instead of read-wait-MFMA
# speedup vs baseline: 1.0098x; 1.0098x over previous
.LBB0_526:
	v_sub_f32_e32 v155, v162, v203
	v_fma_f32 v129, v161, v129, v155
	v_exp_f32_e32 v144, v129
	v_fma_f32 v129, v161, v130, v155
	v_exp_f32_e32 v130, v129
	v_fma_f32 v129, v161, v131, v155
	v_exp_f32_e32 v146, v129
	v_fma_f32 v129, v161, v132, v155
	v_exp_f32_e32 v148, v129
	v_fma_f32 v129, v161, v133, v155
	v_exp_f32_e32 v150, v129
	v_fma_f32 v129, v161, v134, v155
	v_fma_f32 v132, v161, v139, v155
	v_exp_f32_e32 v152, v129
	v_fma_f32 v129, v161, v135, v155
	v_fma_f32 v131, v161, v137, v155
	v_exp_f32_e32 v147, v132
	v_fma_f32 v132, v161, v140, v155
	v_fma_f32 v128, v161, v128, v155
	v_exp_f32_e32 v154, v129
	v_fma_f32 v129, v161, v136, v155
	v_exp_f32_e32 v145, v131
	v_fma_f32 v131, v161, v138, v155
	v_exp_f32_e32 v149, v132
	v_fma_f32 v132, v161, v141, v155
	v_exp_f32_e32 v128, v128
	v_exp_f32_e32 v129, v129
	v_exp_f32_e32 v131, v131
	v_exp_f32_e32 v151, v132
	v_fma_f32 v132, v161, v142, v155
	v_fmac_f32_e32 v155, v161, v143
	v_exp_f32_e32 v153, v132
	v_exp_f32_e32 v155, v155
	v_pk_add_f32 v[132:133], v[128:129], v[144:145]
	v_pk_add_f32 v[134:135], v[130:131], v[146:147]
	v_pk_add_f32 v[136:137], v[152:153], v[154:155]
	v_pk_add_f32 v[132:133], v[132:133], v[134:135]
	v_pk_add_f32 v[134:135], v[148:149], v[150:151]
	s_nop 0
	v_pk_add_f32 v[134:135], v[134:135], v[136:137]
	ds_read_b64_tr_b16 v[136:137], v160 offset:34816
	ds_read_b64_tr_b16 v[138:139], v160 offset:37376
	ds_read_b64_tr_b16 v[140:141], v160 offset:34880
	ds_read_b64_tr_b16 v[142:143], v160 offset:37440
	v_pk_add_f32 v[132:133], v[132:133], v[134:135]
	v_cvt_pk_bf16_f32 v134, v148, v150
	v_add_f32_e32 v132, v132, v133
	v_add_f32_e32 v208, v208, v132
	v_cvt_pk_bf16_f32 v132, v128, v144
	v_cvt_pk_bf16_f32 v133, v130, v146
	v_cvt_pk_bf16_f32 v135, v152, v154
	v_cvt_pk_bf16_f32 v128, v129, v145
	v_cvt_pk_bf16_f32 v129, v131, v147
	v_cvt_pk_bf16_f32 v130, v149, v151
	v_cvt_pk_bf16_f32 v131, v153, v155
	ds_read_b64_tr_b16 v[144:145], v160 offset:34944
	ds_read_b64_tr_b16 v[146:147], v160 offset:37504
	ds_read_b64_tr_b16 v[148:149], v160 offset:35008
	ds_read_b64_tr_b16 v[150:151], v160 offset:37568
	s_waitcnt lgkmcnt(6)
	v_mfma_f32_32x32x16_bf16 v[96:111], v[136:139], v[132:135], v[96:111]
	ds_read_b64_tr_b16 v[136:137], v160 offset:39936
	ds_read_b64_tr_b16 v[138:139], v160 offset:42496
	s_waitcnt lgkmcnt(6)
	v_mfma_f32_32x32x16_bf16 v[80:95], v[140:143], v[132:135], v[80:95]
	ds_read_b64_tr_b16 v[140:141], v160 offset:40000
	ds_read_b64_tr_b16 v[142:143], v160 offset:42560
	s_waitcnt lgkmcnt(6)
	v_mfma_f32_32x32x16_bf16 v[48:63], v[144:147], v[132:135], v[48:63]
	ds_read_b64_tr_b16 v[144:145], v160 offset:40064
	ds_read_b64_tr_b16 v[146:147], v160 offset:42624
	s_waitcnt lgkmcnt(6)
	v_mfma_f32_32x32x16_bf16 v[16:31], v[148:151], v[132:135], v[16:31]
	ds_read_b64_tr_b16 v[148:149], v160 offset:40128
	ds_read_b64_tr_b16 v[150:151], v160 offset:42688
	s_waitcnt lgkmcnt(6)
	v_mfma_f32_32x32x16_bf16 v[96:111], v[136:139], v[128:131], v[96:111]
	s_waitcnt lgkmcnt(4)
	v_mfma_f32_32x32x16_bf16 v[80:95], v[140:143], v[128:131], v[80:95]
	s_waitcnt lgkmcnt(2)
	v_mfma_f32_32x32x16_bf16 v[48:63], v[144:147], v[128:131], v[48:63]
	s_waitcnt lgkmcnt(0)
	v_mfma_f32_32x32x16_bf16 v[16:31], v[148:151], v[128:131], v[16:31]

.LBB0_530:
	s_add_i32 s10, s25, s28
	s_cmp_gt_i32 s10, s26
	s_cbranch_scc1 .LBB0_527
	v_mov_b32_e32 v128, s67
	v_add3_u32 v216, s20, v246, v192
	ds_read_b32 v251, v128
	ds_read_b128 v[160:163], v216
	ds_read_b128 v[164:167], v240
	ds_read_b128 v[168:171], v216 offset:32
	ds_read_b128 v[172:175], v240 offset:32
	ds_read_b128 v[128:131], v216 offset:64
	ds_read_b128 v[132:135], v240 offset:64
	ds_read_b128 v[136:139], v216 offset:96
	ds_read_b128 v[140:143], v240 offset:96
	s_cmpk_gt_i32 s27, 0x7f
	s_cselect_b64 s[10:11], -1, 0
	s_cmpk_lt_i32 s27, 0x80
	v_add_u32_e32 v252, s27, v249
	s_cselect_b64 s[18:19], -1, 0
	s_and_b64 vcc, exec, s[10:11]
	v_add_u32_e32 v253, 63, v252
	s_waitcnt lgkmcnt(6)
	v_mfma_f32_32x32x16_bf16 v[144:159], v[160:163], v[164:167], 0
	ds_read_b128 v[160:163], v216 offset:128
	ds_read_b128 v[164:167], v240 offset:128
	s_waitcnt lgkmcnt(6)
	v_mfma_f32_32x32x16_bf16 v[144:159], v[168:171], v[172:175], v[144:159]
	ds_read_b128 v[168:171], v216 offset:160
	ds_read_b128 v[172:175], v240 offset:160
	s_waitcnt lgkmcnt(6)
	v_mfma_f32_32x32x16_bf16 v[144:159], v[128:131], v[132:135], v[144:159]
	s_waitcnt lgkmcnt(4)
	v_mfma_f32_32x32x16_bf16 v[144:159], v[136:139], v[140:143], v[144:159]
	s_waitcnt lgkmcnt(2)
	v_mfma_f32_32x32x16_bf16 v[128:143], v[160:163], v[164:167], 0
	ds_read_b128 v[160:163], v216 offset:192
	ds_read_b128 v[164:167], v240 offset:192
	s_waitcnt lgkmcnt(2)
	v_mfma_f32_32x32x16_bf16 v[128:143], v[168:171], v[172:175], v[128:143]
	ds_read_b128 v[168:171], v216 offset:224
	ds_read_b128 v[172:175], v240 offset:224
	s_waitcnt lgkmcnt(2)
	v_mfma_f32_32x32x16_bf16 v[128:143], v[160:163], v[164:167], v[128:143]
	s_waitcnt lgkmcnt(0)
	v_mfma_f32_32x32x16_bf16 v[128:143], v[168:171], v[172:175], v[128:143]
	s_nop 1
	s_cbranch_vccnz .LBB0_565
	v_cmp_lt_i32_e32 vcc, -1, v253
	v_mov_b32_e32 v161, 0xff800000
	v_mov_b32_e32 v160, 0xff800000
	s_and_saveexec_b64 s[20:21], vcc
	s_cbranch_execz .LBB0_534
	v_min_u32_e32 v160, 0x80, v253
	v_lshl_add_u32 v160, v160, 2, 0
	v_add_u32_e32 v160, 0x12800, v160
	ds_read_b32 v160, v160
	s_waitcnt lgkmcnt(0)
	v_fmac_f32_e32 v160, 0x3e38aa3b, v144

.LBB0_567:
	v_mov_b32_e32 v160, 0x3e38aa3b
	v_cndmask_b32_e64 v162, 0, v251, s[10:11]
	v_cndmask_b32_e64 v161, 1.0, v160, s[10:11]
	v_sub_f32_e32 v160, v162, v250
	v_fma_f32 v144, v161, v144, v160
	v_exp_f32_e32 v163, v144
	v_fma_f32 v144, v161, v145, v160
	v_exp_f32_e32 v164, v144
	v_fma_f32 v144, v161, v146, v160
	v_exp_f32_e32 v165, v144
	v_fma_f32 v144, v161, v147, v160
	v_exp_f32_e32 v166, v144
	v_fma_f32 v144, v161, v148, v160
	v_exp_f32_e32 v167, v144
	v_fma_f32 v144, v161, v149, v160
	v_exp_f32_e32 v168, v144
	v_fma_f32 v144, v161, v150, v160
	v_exp_f32_e32 v169, v144
	v_fma_f32 v144, v161, v151, v160
	v_exp_f32_e32 v171, v144
	v_fma_f32 v144, v161, v152, v160
	v_exp_f32_e32 v170, v144
	v_fma_f32 v144, v161, v153, v160
	v_exp_f32_e32 v172, v144
	v_fma_f32 v144, v161, v154, v160
	v_exp_f32_e32 v173, v144
	v_fma_f32 v144, v161, v155, v160
	v_exp_f32_e32 v174, v144
	v_fma_f32 v144, v161, v156, v160
	v_exp_f32_e32 v175, v144
	v_fma_f32 v144, v161, v157, v160
	v_exp_f32_e32 v217, v144
	v_fma_f32 v144, v161, v158, v160
	v_fmac_f32_e32 v160, v161, v159
	v_add_u32_e32 v152, s30, v247
	v_exp_f32_e32 v216, v160
	v_add_u32_e32 v160, v152, v248
	ds_read_b64_tr_b16 v[152:153], v160 offset:34816
	ds_read_b64_tr_b16 v[154:155], v160 offset:37376
	v_cvt_pk_bf16_f32 v148, v163, v164
	v_cvt_pk_bf16_f32 v149, v165, v166
	v_cvt_pk_bf16_f32 v150, v167, v168
	v_cvt_pk_bf16_f32 v151, v169, v171
	v_exp_f32_e32 v215, v144
	v_cvt_pk_bf16_f32 v144, v170, v172
	v_cvt_pk_bf16_f32 v145, v173, v174
	v_cvt_pk_bf16_f32 v146, v175, v217
	v_cvt_pk_bf16_f32 v147, v215, v216
	v_add_f32_e32 v156, v163, v164
	v_add_f32_e32 v157, v165, v166
	v_add_f32_e32 v156, v156, v157
	v_add_f32_e32 v157, v167, v168
	v_add_f32_e32 v158, v169, v171
	v_add_f32_e32 v157, v157, v158
	v_add_f32_e32 v156, v156, v157
	v_add_f32_e32 v157, v170, v172
	v_add_f32_e32 v158, v173, v174
	v_add_f32_e32 v157, v157, v158
	v_add_f32_e32 v158, v175, v217
	v_add_f32_e32 v159, v215, v216
	v_add_f32_e32 v158, v158, v159
	v_add_f32_e32 v157, v157, v158
	v_add_f32_e32 v156, v156, v157
	v_add_f32_e32 v209, v209, v156
	s_andn2_b64 vcc, exec, s[18:19]
	ds_read_b64_tr_b16 v[156:157], v160 offset:34880
	ds_read_b64_tr_b16 v[158:159], v160 offset:37440
	ds_read_b64_tr_b16 v[164:165], v160 offset:34944
	ds_read_b64_tr_b16 v[166:167], v160 offset:37504
	ds_read_b64_tr_b16 v[168:169], v160 offset:35008
	ds_read_b64_tr_b16 v[170:171], v160 offset:37568
	s_waitcnt lgkmcnt(6)
	v_mfma_f32_32x32x16_bf16 v[112:127], v[152:155], v[148:151], v[112:127]
	ds_read_b64_tr_b16 v[152:153], v160 offset:39936
	ds_read_b64_tr_b16 v[154:155], v160 offset:42496
	s_waitcnt lgkmcnt(6)
	v_mfma_f32_32x32x16_bf16 v[64:79], v[156:159], v[148:151], v[64:79]
	ds_read_b64_tr_b16 v[156:157], v160 offset:40000
	ds_read_b64_tr_b16 v[158:159], v160 offset:42560
	s_waitcnt lgkmcnt(6)
	v_mfma_f32_32x32x16_bf16 v[32:47], v[164:167], v[148:151], v[32:47]
	ds_read_b64_tr_b16 v[164:165], v160 offset:40064
	ds_read_b64_tr_b16 v[166:167], v160 offset:42624
	s_waitcnt lgkmcnt(6)
	v_mfma_f32_32x32x16_bf16 v[0:15], v[168:171], v[148:151], v[0:15]
	ds_read_b64_tr_b16 v[168:169], v160 offset:40128
	ds_read_b64_tr_b16 v[170:171], v160 offset:42688
	s_waitcnt lgkmcnt(6)
	v_mfma_f32_32x32x16_bf16 v[112:127], v[152:155], v[144:147], v[112:127]
	s_waitcnt lgkmcnt(4)
	v_mfma_f32_32x32x16_bf16 v[64:79], v[156:159], v[144:147], v[64:79]
	s_waitcnt lgkmcnt(2)
	v_mfma_f32_32x32x16_bf16 v[32:47], v[164:167], v[144:147], v[32:47]
	s_waitcnt lgkmcnt(0)
	v_mfma_f32_32x32x16_bf16 v[0:15], v[168:171], v[144:147], v[0:15]
	s_cbranch_vccnz .LBB0_601
	v_cmp_lt_i32_e32 vcc, -1, v253
	v_mov_b32_e32 v145, 0xff800000
	v_mov_b32_e32 v144, 0xff800000
	s_and_saveexec_b64 s[18:19], vcc
	s_cbranch_execz .LBB0_570
	v_min_u32_e32 v144, 0x80, v253
	v_lshl_add_u32 v144, v144, 2, 0
	v_add_u32_e32 v144, 0x12800, v144
	ds_read_b32 v144, v144
	s_waitcnt lgkmcnt(0)
	v_fmac_f32_e32 v144, 0x3e38aa3b, v128
